# speedup vs baseline: 1.0045x; 1.0045x over previous
; __device__ __forceinline__ void epilogue(KP p, f32x4 (&acc)[2][2][4][2], const float* s_inv, const int mode,
;                                          const float* __restrict__ xin, const float resw, const int brow, const int bcol,
;                                          const int pn) {
;     ...
;   if (mode == EPI_GU) {
; #pragma unroll
;     for (int ai = 0; ai < 2; ++ai)
; #pragma unroll
;       for (int m = 0; m < 4; ++m) {
;         const int rl = ai * HALF + wr * 64 + m * 16 + fr;
;         const float sc = rsqrtf((s_inv[rl] + s_inv[256 + rl]) * (1.f / D_) + EPS_);
;         float o[8];
; #pragma unroll
;         for (int n = 0; n < 2; ++n)
; #pragma unroll
;           for (int r = 0; r < 4; ++r) {
;             const float g = acc[ai][0][m][n][r] * sc, u = acc[ai][1][m][n][r] * sc;
;             o[n * 4 + r] = g * __builtin_amdgcn_rcpf(1.f + __expf(-g)) * u;
;           }
;         uint4 ov; ov.x = pack2(o[0], o[1]); ov.y = pack2(o[2], o[3]); ov.z = pack2(o[4], o[5]); ov.w = pack2(o[6], o[7]);
;         *(uint4*)(p->act + (size_t)(brow + rl) * DFF + pn * 128 + wc * 32 + fq * 8) = ov;
;       }
.LBB0_288:
	v_or_b32_e32 v137, v237, v236
	v_lshl_add_u32 v132, v137, 2, s27
	v_add_u32_e32 v133, 0x400, v132
	s_waitcnt lgkmcnt(0)
	ds_read2_b32 v[128:129], v132 offset1:16
	ds_read2_b32 v[130:131], v133 offset1:16
	s_load_dwordx2 s[6:7], s[0:1], 0xb8
	s_lshl_b32 s8, s73, 7
	s_ashr_i32 s9, s8, 31
	s_waitcnt lgkmcnt(0)
	v_mov_b32_e32 v134, v129
	v_mov_b32_e32 v135, v128
	v_mov_b32_e32 v128, v131
	v_mov_b32_e32 v129, v130
	v_pk_add_f32 v[128:129], v[134:135], v[128:129]
	v_mov_b64_e32 v[130:131], s[76:77]
	v_pk_fma_f32 v[134:135], v[128:129], s[58:59], v[130:131] op_sel_hi:[1,0,0]
	s_lshl_b64 s[8:9], s[8:9], 1
	v_mul_f32_e32 v128, 0x4b800000, v135
	v_cmp_gt_f32_e32 vcc, s77, v135
	s_add_u32 s6, s6, s8
	s_addc_u32 s7, s7, s9
	v_cndmask_b32_e32 v128, v135, v128, vcc
	v_rsq_f32_e32 v135, v128
	v_lshlrev_b32_e32 v192, 6, v235
	v_lshl_add_u64 v[128:129], s[6:7], 0, v[192:193]
	v_lshlrev_b32_e32 v192, 4, v234
	v_mul_f32_e32 v136, 0x45800000, v135
	v_cndmask_b32_e32 v136, v135, v136, vcc
	v_pk_mul_f32 v[138:139], v[120:121], v[136:137] op_sel_hi:[1,0]
	v_pk_mul_f32 v[124:125], v[124:125], v[136:137] op_sel_hi:[1,0]
	v_mul_f32_e32 v120, 0xbfb8aa3b, v138
	v_exp_f32_e32 v121, v120
	v_mul_f32_e32 v120, 0xbfb8aa3b, v139
	v_exp_f32_e32 v135, v120
	v_pk_mul_f32 v[112:113], v[112:113], v[136:137] op_sel_hi:[1,0]
	v_add_f32_e32 v121, 1.0, v121
	v_rcp_f32_e32 v140, v121
	v_add_f32_e32 v121, 1.0, v135
	v_rcp_f32_e32 v141, v121
	v_pk_mul_f32 v[126:127], v[126:127], v[136:137] op_sel_hi:[1,0]
	v_pk_mul_f32 v[116:117], v[116:117], v[136:137] op_sel_hi:[1,0]
	v_pk_mul_f32 v[114:115], v[114:115], v[136:137] op_sel_hi:[1,0]
	v_pk_mul_f32 v[138:139], v[138:139], v[140:141]
	v_cmp_gt_f32_e32 vcc, s77, v134
	v_pk_mul_f32 v[124:125], v[124:125], v[138:139]
	v_pk_mul_f32 v[138:139], v[122:123], v[136:137] op_sel_hi:[1,0]
	v_cvt_pk_bf16_f32 v122, v124, v125
	v_mul_f32_e32 v121, 0xbfb8aa3b, v138
	v_exp_f32_e32 v121, v121
	v_mul_f32_e32 v123, 0xbfb8aa3b, v139
	v_exp_f32_e32 v123, v123
	v_add_u32_e32 v120, s24, v137
	v_add_f32_e32 v121, 1.0, v121
	v_rcp_f32_e32 v124, v121
	v_add_f32_e32 v121, 1.0, v123
	v_rcp_f32_e32 v125, v121
	v_mul_f32_e32 v121, 0xbfb8aa3b, v112
	v_exp_f32_e32 v121, v121
	v_mul_f32_e32 v123, 0xbfb8aa3b, v113
	v_exp_f32_e32 v123, v123
	v_pk_mul_f32 v[124:125], v[138:139], v[124:125]
	v_add_f32_e32 v121, 1.0, v121
	v_rcp_f32_e32 v138, v121
	v_add_f32_e32 v121, 1.0, v123
	v_rcp_f32_e32 v139, v121
	v_pk_mul_f32 v[124:125], v[126:127], v[124:125]
	v_lshl_add_u64 v[128:129], v[128:129], 0, v[192:193]
	v_cvt_pk_bf16_f32 v123, v124, v125
	v_pk_mul_f32 v[112:113], v[112:113], v[138:139]
	v_mad_i64_i32 v[142:143], s[6:7], v120, s88, v[128:129]
	v_pk_mul_f32 v[112:113], v[116:117], v[112:113]
	v_mul_f32_e32 v116, 0xbfb8aa3b, v114
	v_cvt_pk_bf16_f32 v124, v112, v113
	v_mul_f32_e32 v112, 0xbfb8aa3b, v115
	v_exp_f32_e32 v116, v116
	v_exp_f32_e32 v113, v112
	v_add_f32_e32 v112, 1.0, v116
	v_add_f32_e32 v113, 1.0, v113
	v_rcp_f32_e32 v112, v112
	v_pk_mul_f32 v[116:117], v[118:119], v[136:137] op_sel_hi:[1,0]
	v_rcp_f32_e32 v113, v113
	v_mul_f32_e32 v118, 0x4b800000, v134
	v_cndmask_b32_e32 v118, v134, v118, vcc
	v_rsq_f32_e32 v118, v118
	v_pk_mul_f32 v[112:113], v[114:115], v[112:113]
	s_nop 0
	v_pk_mul_f32 v[112:113], v[116:117], v[112:113]
	s_nop 0
	v_cvt_pk_bf16_f32 v125, v112, v113
	v_mul_f32_e32 v112, 0x45800000, v118
	v_cndmask_b32_e32 v112, v118, v112, vcc
	v_pk_mul_f32 v[104:105], v[104:105], v[112:113] op_sel_hi:[1,0]
	global_store_dwordx4 v[142:143], v[122:125], off nt
	v_mul_f32_e32 v113, 0xbfb8aa3b, v104
	v_exp_f32_e32 v113, v113
	v_mul_f32_e32 v114, 0xbfb8aa3b, v105
	v_exp_f32_e32 v115, v114
	v_add_f32_e32 v113, 1.0, v113
	v_rcp_f32_e32 v114, v113
	v_pk_mul_f32 v[108:109], v[108:109], v[112:113] op_sel_hi:[1,0]
	v_add_f32_e32 v113, 1.0, v115
	v_pk_mul_f32 v[106:107], v[106:107], v[112:113] op_sel_hi:[1,0]
	v_rcp_f32_e32 v115, v113
	v_mul_f32_e32 v113, 0xbfb8aa3b, v106
	v_exp_f32_e32 v113, v113
	v_mul_f32_e32 v116, 0xbfb8aa3b, v107
	v_exp_f32_e32 v116, v116
	v_pk_mul_f32 v[104:105], v[104:105], v[114:115]
	v_add_f32_e32 v113, 1.0, v113
	v_rcp_f32_e32 v114, v113
	v_add_f32_e32 v113, 1.0, v116
	v_rcp_f32_e32 v115, v113
	v_pk_mul_f32 v[104:105], v[108:109], v[104:105]
	v_pk_mul_f32 v[108:109], v[110:111], v[112:113] op_sel_hi:[1,0]
	v_pk_mul_f32 v[96:97], v[96:97], v[112:113] op_sel_hi:[1,0]
	v_pk_mul_f32 v[106:107], v[106:107], v[114:115]
	v_cvt_pk_bf16_f32 v104, v104, v105
	v_pk_mul_f32 v[106:107], v[108:109], v[106:107]
	v_mul_f32_e32 v105, 0xbfb8aa3b, v96
	v_exp_f32_e32 v108, v105
	v_cvt_pk_bf16_f32 v105, v106, v107
	v_mul_f32_e32 v106, 0xbfb8aa3b, v97
	v_exp_f32_e32 v107, v106
	v_pk_mul_f32 v[98:99], v[98:99], v[112:113] op_sel_hi:[1,0]
	v_add_f32_e32 v106, 1.0, v108
	v_mul_f32_e32 v108, 0xbfb8aa3b, v98
	v_add_f32_e32 v107, 1.0, v107
	v_rcp_f32_e32 v106, v106
	v_rcp_f32_e32 v107, v107
	v_exp_f32_e32 v108, v108
	v_mul_f32_e32 v109, 0xbfb8aa3b, v99
	v_exp_f32_e32 v109, v109
	v_pk_mul_f32 v[96:97], v[96:97], v[106:107]
	v_add_f32_e32 v106, 1.0, v108
	v_rcp_f32_e32 v108, v106
	v_add_f32_e32 v106, 1.0, v109
	v_rcp_f32_e32 v109, v106
	v_pk_mul_f32 v[100:101], v[100:101], v[112:113] op_sel_hi:[1,0]
	v_pk_mul_f32 v[98:99], v[98:99], v[108:109]
	v_pk_mul_f32 v[96:97], v[100:101], v[96:97]
	ds_read2_b32 v[100:101], v132 offset0:32 offset1:48
	v_cvt_pk_bf16_f32 v106, v96, v97
	v_pk_mul_f32 v[96:97], v[102:103], v[112:113] op_sel_hi:[1,0]
	v_add_u32_e32 v102, 16, v120
	v_pk_mul_f32 v[96:97], v[96:97], v[98:99]
	ds_read2_b32 v[98:99], v133 offset0:32 offset1:48
	v_cvt_pk_bf16_f32 v107, v96, v97
	s_waitcnt lgkmcnt(0)
; __device__ __forceinline__ void epilogue(KP p, f32x4 (&acc)[2][2][4][2], const float* s_inv, const int mode,
;                                          const float* __restrict__ xin, const float resw, const int brow, const int bcol,
;                                          const int pn) {
;     ...
;   if (mode == EPI_GU) {
; #pragma unroll
;     for (int ai = 0; ai < 2; ++ai)
; #pragma unroll
;       for (int m = 0; m < 4; ++m) {
;         const int rl = ai * HALF + wr * 64 + m * 16 + fr;
;         const float sc = rsqrtf((s_inv[rl] + s_inv[256 + rl]) * (1.f / D_) + EPS_);
;         float o[8];
; #pragma unroll
;         for (int n = 0; n < 2; ++n)
; #pragma unroll
;           for (int r = 0; r < 4; ++r) {
;             const float g = acc[ai][0][m][n][r] * sc, u = acc[ai][1][m][n][r] * sc;
;             o[n * 4 + r] = g * __builtin_amdgcn_rcpf(1.f + __expf(-g)) * u;
;           }
;         uint4 ov; ov.x = pack2(o[0], o[1]); ov.y = pack2(o[2], o[3]); ov.z = pack2(o[4], o[5]); ov.w = pack2(o[6], o[7]);
;         *(uint4*)(p->act + (size_t)(brow + rl) * DFF + pn * 128 + wc * 32 + fq * 8) = ov;
;       }
	v_mov_b32_e32 v96, v101
	v_mov_b32_e32 v97, v100
	v_mov_b32_e32 v100, v99
	v_mov_b32_e32 v101, v98
	v_pk_add_f32 v[96:97], v[96:97], v[100:101]
	s_nop 0
	v_pk_fma_f32 v[96:97], v[96:97], s[58:59], v[130:131] op_sel_hi:[1,0,0]
	s_nop 0
	v_mul_f32_e32 v98, 0x4b800000, v97
	v_cmp_gt_f32_e32 vcc, s77, v97
	s_nop 1
	v_cndmask_b32_e32 v97, v97, v98, vcc
	v_rsq_f32_e32 v97, v97
	v_mad_i64_i32 v[98:99], s[6:7], v102, s88, v[128:129]
	global_store_dwordx4 v[98:99], v[104:107], off nt
	v_mul_f32_e32 v98, 0x45800000, v97
	v_cndmask_b32_e32 v98, v97, v98, vcc
	v_pk_mul_f32 v[88:89], v[88:89], v[98:99] op_sel_hi:[1,0]
	v_cmp_gt_f32_e32 vcc, s77, v96
	v_mul_f32_e32 v97, 0xbfb8aa3b, v88
	v_exp_f32_e32 v97, v97
	v_mul_f32_e32 v99, 0xbfb8aa3b, v89
	v_exp_f32_e32 v99, v99
	v_add_u32_e32 v102, 32, v120
	v_add_f32_e32 v97, 1.0, v97
	v_rcp_f32_e32 v100, v97
	v_add_f32_e32 v97, 1.0, v99
	v_rcp_f32_e32 v101, v97
	v_pk_mul_f32 v[92:93], v[92:93], v[98:99] op_sel_hi:[1,0]
	v_pk_mul_f32 v[90:91], v[90:91], v[98:99] op_sel_hi:[1,0]
	v_pk_mul_f32 v[80:81], v[80:81], v[98:99] op_sel_hi:[1,0]
	v_pk_mul_f32 v[88:89], v[88:89], v[100:101]
	v_mul_f32_e32 v97, 0xbfb8aa3b, v81
	v_pk_mul_f32 v[88:89], v[92:93], v[88:89]
	v_mul_f32_e32 v92, 0xbfb8aa3b, v90
	v_cvt_pk_bf16_f32 v88, v88, v89
	v_mul_f32_e32 v89, 0xbfb8aa3b, v91
	v_exp_f32_e32 v89, v89
	v_exp_f32_e32 v92, v92
	v_exp_f32_e32 v97, v97
	v_pk_mul_f32 v[94:95], v[94:95], v[98:99] op_sel_hi:[1,0]
	v_add_f32_e32 v89, 1.0, v89
	v_rcp_f32_e32 v93, v89
	v_mul_f32_e32 v89, 0xbfb8aa3b, v80
	v_add_f32_e32 v92, 1.0, v92
	v_exp_f32_e32 v89, v89
	v_rcp_f32_e32 v92, v92
	v_pk_mul_f32 v[84:85], v[84:85], v[98:99] op_sel_hi:[1,0]
	v_pk_mul_f32 v[82:83], v[82:83], v[98:99] op_sel_hi:[1,0]
	v_add_f32_e32 v89, 1.0, v89
	v_pk_mul_f32 v[90:91], v[90:91], v[92:93]
	v_rcp_f32_e32 v92, v89
	v_add_f32_e32 v89, 1.0, v97
	v_rcp_f32_e32 v93, v89
	v_pk_mul_f32 v[90:91], v[94:95], v[90:91]
	v_mad_i64_i32 v[102:103], s[6:7], v102, s88, v[128:129]
	v_pk_mul_f32 v[80:81], v[80:81], v[92:93]
	v_cvt_pk_bf16_f32 v89, v90, v91
	v_pk_mul_f32 v[80:81], v[84:85], v[80:81]
	v_mul_f32_e32 v84, 0xbfb8aa3b, v82
	v_cvt_pk_bf16_f32 v90, v80, v81
	v_mul_f32_e32 v80, 0xbfb8aa3b, v83
	v_exp_f32_e32 v84, v84
	v_exp_f32_e32 v81, v80
	v_add_f32_e32 v80, 1.0, v84
	v_add_f32_e32 v81, 1.0, v81
	v_rcp_f32_e32 v80, v80
	v_pk_mul_f32 v[84:85], v[86:87], v[98:99] op_sel_hi:[1,0]
	v_rcp_f32_e32 v81, v81
	v_mul_f32_e32 v86, 0x4b800000, v96
	v_cndmask_b32_e32 v86, v96, v86, vcc
	v_rsq_f32_e32 v86, v86
	v_pk_mul_f32 v[80:81], v[82:83], v[80:81]
	s_nop 0
	v_pk_mul_f32 v[80:81], v[84:85], v[80:81]
	s_nop 0
	v_cvt_pk_bf16_f32 v91, v80, v81
	v_mul_f32_e32 v80, 0x45800000, v86
	v_cndmask_b32_e32 v80, v86, v80, vcc
	v_pk_mul_f32 v[72:73], v[72:73], v[80:81] op_sel_hi:[1,0]
	global_store_dwordx4 v[102:103], v[88:91], off nt
	v_mul_f32_e32 v81, 0xbfb8aa3b, v72
	v_exp_f32_e32 v81, v81
	v_mul_f32_e32 v82, 0xbfb8aa3b, v73
	v_exp_f32_e32 v83, v82
	v_add_f32_e32 v81, 1.0, v81
	v_rcp_f32_e32 v82, v81
	v_pk_mul_f32 v[76:77], v[76:77], v[80:81] op_sel_hi:[1,0]
	v_add_f32_e32 v81, 1.0, v83
	v_pk_mul_f32 v[74:75], v[74:75], v[80:81] op_sel_hi:[1,0]
	v_rcp_f32_e32 v83, v81
	v_mul_f32_e32 v81, 0xbfb8aa3b, v74
	v_exp_f32_e32 v81, v81
	v_mul_f32_e32 v84, 0xbfb8aa3b, v75
	v_exp_f32_e32 v84, v84
	v_pk_mul_f32 v[72:73], v[72:73], v[82:83]
	v_add_f32_e32 v81, 1.0, v81
	v_rcp_f32_e32 v82, v81
	v_add_f32_e32 v81, 1.0, v84
	v_rcp_f32_e32 v83, v81
	v_pk_mul_f32 v[72:73], v[76:77], v[72:73]
	v_pk_mul_f32 v[76:77], v[78:79], v[80:81] op_sel_hi:[1,0]
	v_pk_mul_f32 v[64:65], v[64:65], v[80:81] op_sel_hi:[1,0]
	v_pk_mul_f32 v[74:75], v[74:75], v[82:83]
	v_cvt_pk_bf16_f32 v72, v72, v73
	v_pk_mul_f32 v[74:75], v[76:77], v[74:75]
	v_mul_f32_e32 v73, 0xbfb8aa3b, v64
	v_exp_f32_e32 v76, v73
	v_cvt_pk_bf16_f32 v73, v74, v75
	v_mul_f32_e32 v74, 0xbfb8aa3b, v65
	v_exp_f32_e32 v75, v74
	v_pk_mul_f32 v[66:67], v[66:67], v[80:81] op_sel_hi:[1,0]
	v_add_f32_e32 v74, 1.0, v76
	v_mul_f32_e32 v76, 0xbfb8aa3b, v66
	v_add_f32_e32 v75, 1.0, v75
	v_rcp_f32_e32 v74, v74
	v_rcp_f32_e32 v75, v75
	v_exp_f32_e32 v76, v76
	v_mul_f32_e32 v77, 0xbfb8aa3b, v67
	v_exp_f32_e32 v77, v77
	v_pk_mul_f32 v[64:65], v[64:65], v[74:75]
	v_add_f32_e32 v74, 1.0, v76
	v_rcp_f32_e32 v76, v74
	v_add_f32_e32 v74, 1.0, v77
	v_rcp_f32_e32 v77, v74
	v_pk_mul_f32 v[68:69], v[68:69], v[80:81] op_sel_hi:[1,0]
	v_pk_mul_f32 v[66:67], v[66:67], v[76:77]
	v_pk_mul_f32 v[64:65], v[68:69], v[64:65]
	ds_read2_b32 v[68:69], v132 offset0:128 offset1:144
	v_cvt_pk_bf16_f32 v74, v64, v65
	v_pk_mul_f32 v[64:65], v[70:71], v[80:81] op_sel_hi:[1,0]
	v_add_u32_e32 v70, 48, v120
	v_pk_mul_f32 v[64:65], v[64:65], v[66:67]
	ds_read2_b32 v[66:67], v133 offset0:128 offset1:144
	v_cvt_pk_bf16_f32 v75, v64, v65
	s_waitcnt lgkmcnt(0)
; __device__ __forceinline__ void epilogue(KP p, f32x4 (&acc)[2][2][4][2], const float* s_inv, const int mode,
;                                          const float* __restrict__ xin, const float resw, const int brow, const int bcol,
;                                          const int pn) {
;     ...
;   if (mode == EPI_GU) {
; #pragma unroll
;     for (int ai = 0; ai < 2; ++ai)
; #pragma unroll
;       for (int m = 0; m < 4; ++m) {
;         const int rl = ai * HALF + wr * 64 + m * 16 + fr;
;         const float sc = rsqrtf((s_inv[rl] + s_inv[256 + rl]) * (1.f / D_) + EPS_);
;         float o[8];
; #pragma unroll
;         for (int n = 0; n < 2; ++n)
; #pragma unroll
;           for (int r = 0; r < 4; ++r) {
;             const float g = acc[ai][0][m][n][r] * sc, u = acc[ai][1][m][n][r] * sc;
;             o[n * 4 + r] = g * __builtin_amdgcn_rcpf(1.f + __expf(-g)) * u;
;           }
;         uint4 ov; ov.x = pack2(o[0], o[1]); ov.y = pack2(o[2], o[3]); ov.z = pack2(o[4], o[5]); ov.w = pack2(o[6], o[7]);
;         *(uint4*)(p->act + (size_t)(brow + rl) * DFF + pn * 128 + wc * 32 + fq * 8) = ov;
;       }
	v_mov_b32_e32 v64, v69
	v_mov_b32_e32 v65, v68
	v_mov_b32_e32 v68, v67
	v_mov_b32_e32 v69, v66
	v_pk_add_f32 v[64:65], v[64:65], v[68:69]
	s_nop 0
	v_pk_fma_f32 v[64:65], v[64:65], s[58:59], v[130:131] op_sel_hi:[1,0,0]
	s_nop 0
	v_mul_f32_e32 v66, 0x4b800000, v65
	v_cmp_gt_f32_e32 vcc, s77, v65
	s_nop 1
	v_cndmask_b32_e32 v65, v65, v66, vcc
	v_rsq_f32_e32 v65, v65
	v_mad_i64_i32 v[66:67], s[6:7], v70, s88, v[128:129]
	global_store_dwordx4 v[66:67], v[72:75], off nt
	v_mul_f32_e32 v66, 0x45800000, v65
	v_cndmask_b32_e32 v66, v65, v66, vcc
	v_pk_mul_f32 v[56:57], v[56:57], v[66:67] op_sel_hi:[1,0]
	v_cmp_gt_f32_e32 vcc, s77, v64
	v_mul_f32_e32 v65, 0xbfb8aa3b, v56
	v_exp_f32_e32 v65, v65
	v_mul_f32_e32 v67, 0xbfb8aa3b, v57
	v_exp_f32_e32 v67, v67
	v_add_u32_e32 v70, 0x80, v120
	v_add_f32_e32 v65, 1.0, v65
	v_rcp_f32_e32 v68, v65
	v_add_f32_e32 v65, 1.0, v67
	v_rcp_f32_e32 v69, v65
	v_pk_mul_f32 v[60:61], v[60:61], v[66:67] op_sel_hi:[1,0]
	v_pk_mul_f32 v[58:59], v[58:59], v[66:67] op_sel_hi:[1,0]
	v_pk_mul_f32 v[48:49], v[48:49], v[66:67] op_sel_hi:[1,0]
	v_pk_mul_f32 v[56:57], v[56:57], v[68:69]
	v_mul_f32_e32 v65, 0xbfb8aa3b, v49
	v_pk_mul_f32 v[56:57], v[60:61], v[56:57]
	v_mul_f32_e32 v60, 0xbfb8aa3b, v58
	v_cvt_pk_bf16_f32 v56, v56, v57
	v_mul_f32_e32 v57, 0xbfb8aa3b, v59
	v_exp_f32_e32 v57, v57
	v_exp_f32_e32 v60, v60
	v_exp_f32_e32 v65, v65
	v_pk_mul_f32 v[62:63], v[62:63], v[66:67] op_sel_hi:[1,0]
	v_add_f32_e32 v57, 1.0, v57
	v_rcp_f32_e32 v61, v57
	v_mul_f32_e32 v57, 0xbfb8aa3b, v48
	v_add_f32_e32 v60, 1.0, v60
	v_exp_f32_e32 v57, v57
	v_rcp_f32_e32 v60, v60
	v_pk_mul_f32 v[52:53], v[52:53], v[66:67] op_sel_hi:[1,0]
	v_pk_mul_f32 v[50:51], v[50:51], v[66:67] op_sel_hi:[1,0]
	v_add_f32_e32 v57, 1.0, v57
	v_pk_mul_f32 v[58:59], v[58:59], v[60:61]
	v_rcp_f32_e32 v60, v57
	v_add_f32_e32 v57, 1.0, v65
	v_rcp_f32_e32 v61, v57
	v_pk_mul_f32 v[58:59], v[62:63], v[58:59]
	v_mad_i64_i32 v[70:71], s[6:7], v70, s88, v[128:129]
	v_pk_mul_f32 v[48:49], v[48:49], v[60:61]
	v_cvt_pk_bf16_f32 v57, v58, v59
	v_pk_mul_f32 v[48:49], v[52:53], v[48:49]
	v_mul_f32_e32 v52, 0xbfb8aa3b, v50
	v_cvt_pk_bf16_f32 v58, v48, v49
	v_mul_f32_e32 v48, 0xbfb8aa3b, v51
	v_exp_f32_e32 v52, v52
	v_exp_f32_e32 v49, v48
	v_add_f32_e32 v48, 1.0, v52
	v_add_f32_e32 v49, 1.0, v49
	v_rcp_f32_e32 v48, v48
	v_pk_mul_f32 v[52:53], v[54:55], v[66:67] op_sel_hi:[1,0]
	v_rcp_f32_e32 v49, v49
	v_mul_f32_e32 v54, 0x4b800000, v64
	v_cndmask_b32_e32 v54, v64, v54, vcc
	v_rsq_f32_e32 v54, v54
	v_pk_mul_f32 v[48:49], v[50:51], v[48:49]
	s_nop 0
	v_pk_mul_f32 v[48:49], v[52:53], v[48:49]
	s_nop 0
	v_cvt_pk_bf16_f32 v59, v48, v49
	v_mul_f32_e32 v48, 0x45800000, v54
	v_cndmask_b32_e32 v48, v54, v48, vcc
	v_pk_mul_f32 v[40:41], v[40:41], v[48:49] op_sel_hi:[1,0]
	global_store_dwordx4 v[70:71], v[56:59], off nt
	v_mul_f32_e32 v49, 0xbfb8aa3b, v40
	v_exp_f32_e32 v49, v49
	v_mul_f32_e32 v50, 0xbfb8aa3b, v41
	v_exp_f32_e32 v51, v50
	v_add_f32_e32 v49, 1.0, v49
	v_rcp_f32_e32 v50, v49
	v_pk_mul_f32 v[44:45], v[44:45], v[48:49] op_sel_hi:[1,0]
	v_add_f32_e32 v49, 1.0, v51
	v_pk_mul_f32 v[42:43], v[42:43], v[48:49] op_sel_hi:[1,0]
	v_rcp_f32_e32 v51, v49
	v_mul_f32_e32 v49, 0xbfb8aa3b, v42
	v_exp_f32_e32 v49, v49
	v_mul_f32_e32 v52, 0xbfb8aa3b, v43
	v_exp_f32_e32 v52, v52
	v_pk_mul_f32 v[40:41], v[40:41], v[50:51]
	v_add_f32_e32 v49, 1.0, v49
	v_rcp_f32_e32 v50, v49
	v_add_f32_e32 v49, 1.0, v52
	v_rcp_f32_e32 v51, v49
	v_pk_mul_f32 v[40:41], v[44:45], v[40:41]
	v_pk_mul_f32 v[44:45], v[46:47], v[48:49] op_sel_hi:[1,0]
	v_pk_mul_f32 v[32:33], v[32:33], v[48:49] op_sel_hi:[1,0]
	v_pk_mul_f32 v[42:43], v[42:43], v[50:51]
	v_cvt_pk_bf16_f32 v40, v40, v41
	v_pk_mul_f32 v[42:43], v[44:45], v[42:43]
	v_mul_f32_e32 v41, 0xbfb8aa3b, v32
	v_exp_f32_e32 v44, v41
	v_cvt_pk_bf16_f32 v41, v42, v43
	v_mul_f32_e32 v42, 0xbfb8aa3b, v33
	v_exp_f32_e32 v43, v42
	v_pk_mul_f32 v[34:35], v[34:35], v[48:49] op_sel_hi:[1,0]
	v_add_f32_e32 v42, 1.0, v44
	v_mul_f32_e32 v44, 0xbfb8aa3b, v34
	v_add_f32_e32 v43, 1.0, v43
	v_rcp_f32_e32 v42, v42
	v_rcp_f32_e32 v43, v43
	v_exp_f32_e32 v44, v44
	v_mul_f32_e32 v45, 0xbfb8aa3b, v35
	v_exp_f32_e32 v45, v45
	v_pk_mul_f32 v[32:33], v[32:33], v[42:43]
	v_add_f32_e32 v42, 1.0, v44
	v_rcp_f32_e32 v44, v42
	v_add_f32_e32 v42, 1.0, v45
	v_rcp_f32_e32 v45, v42
	v_pk_mul_f32 v[36:37], v[36:37], v[48:49] op_sel_hi:[1,0]
	v_pk_mul_f32 v[34:35], v[34:35], v[44:45]
	v_pk_mul_f32 v[32:33], v[36:37], v[32:33]
	ds_read2_b32 v[36:37], v132 offset0:160 offset1:176
	v_cvt_pk_bf16_f32 v42, v32, v33
	v_pk_mul_f32 v[32:33], v[38:39], v[48:49] op_sel_hi:[1,0]
	v_add_u32_e32 v38, 0x90, v120
	v_pk_mul_f32 v[32:33], v[32:33], v[34:35]
	ds_read2_b32 v[34:35], v133 offset0:160 offset1:176
	v_cvt_pk_bf16_f32 v43, v32, v33
	s_waitcnt lgkmcnt(0)
; __device__ __forceinline__ void epilogue(KP p, f32x4 (&acc)[2][2][4][2], const float* s_inv, const int mode,
;                                          const float* __restrict__ xin, const float resw, const int brow, const int bcol,
;                                          const int pn) {
;     ...
;   if (mode == EPI_GU) {
; #pragma unroll
;     for (int ai = 0; ai < 2; ++ai)
; #pragma unroll
;       for (int m = 0; m < 4; ++m) {
;         const int rl = ai * HALF + wr * 64 + m * 16 + fr;
;         const float sc = rsqrtf((s_inv[rl] + s_inv[256 + rl]) * (1.f / D_) + EPS_);
;         float o[8];
; #pragma unroll
;         for (int n = 0; n < 2; ++n)
; #pragma unroll
;           for (int r = 0; r < 4; ++r) {
;             const float g = acc[ai][0][m][n][r] * sc, u = acc[ai][1][m][n][r] * sc;
;             o[n * 4 + r] = g * __builtin_amdgcn_rcpf(1.f + __expf(-g)) * u;
;           }
;         uint4 ov; ov.x = pack2(o[0], o[1]); ov.y = pack2(o[2], o[3]); ov.z = pack2(o[4], o[5]); ov.w = pack2(o[6], o[7]);
;         *(uint4*)(p->act + (size_t)(brow + rl) * DFF + pn * 128 + wc * 32 + fq * 8) = ov;
;       }
	v_mov_b32_e32 v32, v37
	v_mov_b32_e32 v33, v36
	v_mov_b32_e32 v36, v35
	v_mov_b32_e32 v37, v34
	v_pk_add_f32 v[32:33], v[32:33], v[36:37]
	s_nop 0
	v_pk_fma_f32 v[32:33], v[32:33], s[58:59], v[130:131] op_sel_hi:[1,0,0]
	s_nop 0
	v_mul_f32_e32 v34, 0x4b800000, v33
	v_cmp_gt_f32_e32 vcc, s77, v33
	s_nop 1
	v_cndmask_b32_e32 v33, v33, v34, vcc
	v_rsq_f32_e32 v33, v33
	v_mad_i64_i32 v[34:35], s[6:7], v38, s88, v[128:129]
	global_store_dwordx4 v[34:35], v[40:43], off nt
	v_mul_f32_e32 v34, 0x45800000, v33
	v_cndmask_b32_e32 v34, v33, v34, vcc
	v_pk_mul_f32 v[24:25], v[24:25], v[34:35] op_sel_hi:[1,0]
	v_cmp_gt_f32_e32 vcc, s77, v32
	v_mul_f32_e32 v33, 0xbfb8aa3b, v24
	v_exp_f32_e32 v33, v33
	v_mul_f32_e32 v35, 0xbfb8aa3b, v25
	v_exp_f32_e32 v35, v35
	v_add_u32_e32 v38, 0xa0, v120
	v_add_f32_e32 v33, 1.0, v33
	v_rcp_f32_e32 v36, v33
	v_add_f32_e32 v33, 1.0, v35
	v_rcp_f32_e32 v37, v33
	v_pk_mul_f32 v[28:29], v[28:29], v[34:35] op_sel_hi:[1,0]
	v_pk_mul_f32 v[26:27], v[26:27], v[34:35] op_sel_hi:[1,0]
	v_pk_mul_f32 v[16:17], v[16:17], v[34:35] op_sel_hi:[1,0]
	v_pk_mul_f32 v[24:25], v[24:25], v[36:37]
	v_mul_f32_e32 v33, 0xbfb8aa3b, v17
	v_pk_mul_f32 v[24:25], v[28:29], v[24:25]
	v_mul_f32_e32 v28, 0xbfb8aa3b, v26
	v_cvt_pk_bf16_f32 v24, v24, v25
	v_mul_f32_e32 v25, 0xbfb8aa3b, v27
	v_exp_f32_e32 v25, v25
	v_exp_f32_e32 v28, v28
	v_exp_f32_e32 v33, v33
	v_pk_mul_f32 v[30:31], v[30:31], v[34:35] op_sel_hi:[1,0]
	v_add_f32_e32 v25, 1.0, v25
	v_rcp_f32_e32 v29, v25
	v_mul_f32_e32 v25, 0xbfb8aa3b, v16
	v_add_f32_e32 v28, 1.0, v28
	v_exp_f32_e32 v25, v25
	v_rcp_f32_e32 v28, v28
	v_pk_mul_f32 v[20:21], v[20:21], v[34:35] op_sel_hi:[1,0]
	v_pk_mul_f32 v[18:19], v[18:19], v[34:35] op_sel_hi:[1,0]
	v_add_f32_e32 v25, 1.0, v25
	v_pk_mul_f32 v[26:27], v[26:27], v[28:29]
	v_rcp_f32_e32 v28, v25
	v_add_f32_e32 v25, 1.0, v33
	v_rcp_f32_e32 v29, v25
	v_pk_mul_f32 v[26:27], v[30:31], v[26:27]
	v_mad_i64_i32 v[38:39], s[6:7], v38, s88, v[128:129]
	v_pk_mul_f32 v[16:17], v[16:17], v[28:29]
	v_cvt_pk_bf16_f32 v25, v26, v27
	v_pk_mul_f32 v[16:17], v[20:21], v[16:17]
	v_mul_f32_e32 v20, 0xbfb8aa3b, v18
	v_cvt_pk_bf16_f32 v26, v16, v17
	v_mul_f32_e32 v16, 0xbfb8aa3b, v19
	v_exp_f32_e32 v20, v20
	v_exp_f32_e32 v17, v16
	v_add_f32_e32 v16, 1.0, v20
	v_add_f32_e32 v17, 1.0, v17
	v_rcp_f32_e32 v16, v16
	v_pk_mul_f32 v[20:21], v[22:23], v[34:35] op_sel_hi:[1,0]
	v_rcp_f32_e32 v17, v17
	v_mul_f32_e32 v22, 0x4b800000, v32
	v_cndmask_b32_e32 v22, v32, v22, vcc
	v_rsq_f32_e32 v22, v22
	v_pk_mul_f32 v[16:17], v[18:19], v[16:17]
	s_nop 0
	v_pk_mul_f32 v[16:17], v[20:21], v[16:17]
	s_nop 0
	v_cvt_pk_bf16_f32 v27, v16, v17
	v_mul_f32_e32 v16, 0x45800000, v22
	v_cndmask_b32_e32 v16, v22, v16, vcc
	v_pk_mul_f32 v[8:9], v[8:9], v[16:17] op_sel_hi:[1,0]
	global_store_dwordx4 v[38:39], v[24:27], off nt
	v_mul_f32_e32 v17, 0xbfb8aa3b, v8
	v_exp_f32_e32 v17, v17
	v_mul_f32_e32 v18, 0xbfb8aa3b, v9
	v_exp_f32_e32 v19, v18
	v_add_f32_e32 v17, 1.0, v17
	v_rcp_f32_e32 v18, v17
	v_pk_mul_f32 v[12:13], v[12:13], v[16:17] op_sel_hi:[1,0]
	v_add_f32_e32 v17, 1.0, v19
	v_pk_mul_f32 v[10:11], v[10:11], v[16:17] op_sel_hi:[1,0]
	v_rcp_f32_e32 v19, v17
	v_mul_f32_e32 v17, 0xbfb8aa3b, v10
	v_exp_f32_e32 v17, v17
	v_mul_f32_e32 v20, 0xbfb8aa3b, v11
	v_exp_f32_e32 v20, v20
	v_pk_mul_f32 v[8:9], v[8:9], v[18:19]
	v_add_f32_e32 v17, 1.0, v17
	v_rcp_f32_e32 v18, v17
	v_add_f32_e32 v17, 1.0, v20
	v_rcp_f32_e32 v19, v17
	v_pk_mul_f32 v[8:9], v[12:13], v[8:9]
	v_pk_mul_f32 v[12:13], v[14:15], v[16:17] op_sel_hi:[1,0]
	v_pk_mul_f32 v[0:1], v[0:1], v[16:17] op_sel_hi:[1,0]
	v_pk_mul_f32 v[10:11], v[10:11], v[18:19]
	v_cvt_pk_bf16_f32 v8, v8, v9
	v_pk_mul_f32 v[10:11], v[12:13], v[10:11]
	v_mul_f32_e32 v9, 0xbfb8aa3b, v0
	v_exp_f32_e32 v12, v9
	v_cvt_pk_bf16_f32 v9, v10, v11
	v_mul_f32_e32 v10, 0xbfb8aa3b, v1
	v_exp_f32_e32 v11, v10
	v_pk_mul_f32 v[2:3], v[2:3], v[16:17] op_sel_hi:[1,0]
	v_add_f32_e32 v10, 1.0, v12
	v_mul_f32_e32 v12, 0xbfb8aa3b, v2
	v_add_f32_e32 v11, 1.0, v11
	v_rcp_f32_e32 v10, v10
	v_rcp_f32_e32 v11, v11
	v_exp_f32_e32 v12, v12
	v_mul_f32_e32 v13, 0xbfb8aa3b, v3
	v_exp_f32_e32 v13, v13
	v_pk_mul_f32 v[0:1], v[0:1], v[10:11]
	v_add_f32_e32 v10, 1.0, v12
	v_rcp_f32_e32 v12, v10
	v_add_f32_e32 v10, 1.0, v13
	v_rcp_f32_e32 v13, v10
	v_pk_mul_f32 v[4:5], v[4:5], v[16:17] op_sel_hi:[1,0]
	v_pk_mul_f32 v[2:3], v[2:3], v[12:13]
	v_pk_mul_f32 v[0:1], v[4:5], v[0:1]
	s_nop 0
	v_cvt_pk_bf16_f32 v10, v0, v1
	v_pk_mul_f32 v[0:1], v[6:7], v[16:17] op_sel_hi:[1,0]
	s_nop 0
	v_pk_mul_f32 v[0:1], v[0:1], v[2:3]
	s_nop 0
	v_cvt_pk_bf16_f32 v11, v0, v1
	v_add_u32_e32 v0, 0xb0, v120
	v_mad_i64_i32 v[0:1], s[6:7], v0, s88, v[128:129]
	global_store_dwordx4 v[0:1], v[8:11], off nt
	s_and_b64 vcc, exec, s[4:5]
	s_cbranch_vccnz .LBB0_46
	s_branch .LBB0_314
